# 256-byte alignment of the attention loop head and the three GEMM K-loop heads (instruction fetch placement)
# baseline (speedup 1.0000x reference)
.LBB0_258:
	s_and_b64 s[26:27], s[56:57], exec
	s_cselect_b32 s6, s53, s11
	s_cselect_b32 s36, s52, s10
	s_cselect_b32 s37, s55, s15
	s_cselect_b32 s40, s54, s14
	s_add_u32 s10, s10, 0x40080
	s_addc_u32 s11, s11, 0
	s_add_u32 s41, s14, 0x100
	v_mov_b32_e32 v2, 0
	s_addc_u32 s43, s15, 0
	s_mov_b32 s49, -2
	v_mov_b32_e32 v3, v2
	v_mov_b32_e32 v4, v2
	v_mov_b32_e32 v5, v2
	v_mov_b32_e32 v6, v2
	v_mov_b32_e32 v7, v2
	v_mov_b32_e32 v8, v2
	v_mov_b32_e32 v9, v2
	v_mov_b32_e32 v18, v2
	v_mov_b32_e32 v19, v2
	v_mov_b32_e32 v20, v2
	v_mov_b32_e32 v21, v2
	v_mov_b32_e32 v22, v2
	v_mov_b32_e32 v23, v2
	v_mov_b32_e32 v24, v2
	v_mov_b32_e32 v25, v2
	v_mov_b32_e32 v34, v2
	v_mov_b32_e32 v35, v2
	v_mov_b32_e32 v36, v2
	v_mov_b32_e32 v37, v2
	v_mov_b32_e32 v38, v2
	v_mov_b32_e32 v39, v2
	v_mov_b32_e32 v40, v2
	v_mov_b32_e32 v41, v2
	v_mov_b32_e32 v50, v2
	v_mov_b32_e32 v51, v2
	v_mov_b32_e32 v52, v2
	v_mov_b32_e32 v53, v2
	v_mov_b32_e32 v54, v2
	v_mov_b32_e32 v55, v2
	v_mov_b32_e32 v56, v2
	v_mov_b32_e32 v57, v2
	v_mov_b32_e32 v10, v2
	v_mov_b32_e32 v11, v2
	v_mov_b32_e32 v12, v2
	v_mov_b32_e32 v13, v2
	v_mov_b32_e32 v14, v2
	v_mov_b32_e32 v15, v2
	v_mov_b32_e32 v16, v2
	v_mov_b32_e32 v17, v2
	v_mov_b32_e32 v26, v2
	v_mov_b32_e32 v27, v2
	v_mov_b32_e32 v28, v2
	v_mov_b32_e32 v29, v2
	v_mov_b32_e32 v30, v2
	v_mov_b32_e32 v31, v2
	v_mov_b32_e32 v32, v2
	v_mov_b32_e32 v33, v2
	v_mov_b32_e32 v42, v2
	v_mov_b32_e32 v43, v2
	v_mov_b32_e32 v44, v2
	v_mov_b32_e32 v45, v2
	v_mov_b32_e32 v46, v2
	v_mov_b32_e32 v47, v2
	v_mov_b32_e32 v48, v2
	v_mov_b32_e32 v49, v2
	v_mov_b32_e32 v58, v2
	v_mov_b32_e32 v59, v2
	v_mov_b32_e32 v60, v2
	v_mov_b32_e32 v61, v2
	v_mov_b32_e32 v62, v2
	v_mov_b32_e32 v63, v2
	v_mov_b32_e32 v64, v2
	v_mov_b32_e32 v65, v2
	v_mov_b32_e32 v66, v2
	v_mov_b32_e32 v67, v2
	v_mov_b32_e32 v68, v2
	v_mov_b32_e32 v69, v2
	v_mov_b32_e32 v70, v2
	v_mov_b32_e32 v71, v2
	v_mov_b32_e32 v72, v2
	v_mov_b32_e32 v73, v2
	v_mov_b32_e32 v82, v2
	v_mov_b32_e32 v83, v2
	v_mov_b32_e32 v84, v2
	v_mov_b32_e32 v85, v2
	v_mov_b32_e32 v86, v2
	v_mov_b32_e32 v87, v2
	v_mov_b32_e32 v88, v2
	v_mov_b32_e32 v89, v2
	v_mov_b32_e32 v98, v2
	v_mov_b32_e32 v99, v2
	v_mov_b32_e32 v100, v2
	v_mov_b32_e32 v101, v2
	v_mov_b32_e32 v102, v2
	v_mov_b32_e32 v103, v2
	v_mov_b32_e32 v104, v2
	v_mov_b32_e32 v105, v2
	v_mov_b32_e32 v114, v2
	v_mov_b32_e32 v115, v2
	v_mov_b32_e32 v116, v2
	v_mov_b32_e32 v117, v2
	v_mov_b32_e32 v118, v2
	v_mov_b32_e32 v119, v2
	v_mov_b32_e32 v120, v2
	v_mov_b32_e32 v121, v2
	v_mov_b32_e32 v74, v2
	v_mov_b32_e32 v75, v2
	v_mov_b32_e32 v76, v2
	v_mov_b32_e32 v77, v2
	v_mov_b32_e32 v78, v2
	v_mov_b32_e32 v79, v2
	v_mov_b32_e32 v80, v2
	v_mov_b32_e32 v81, v2
	v_mov_b32_e32 v90, v2
	v_mov_b32_e32 v91, v2
	v_mov_b32_e32 v92, v2
	v_mov_b32_e32 v93, v2
	v_mov_b32_e32 v94, v2
	v_mov_b32_e32 v95, v2
	v_mov_b32_e32 v96, v2
	v_mov_b32_e32 v97, v2
	v_mov_b32_e32 v106, v2
	v_mov_b32_e32 v107, v2
	v_mov_b32_e32 v108, v2
	v_mov_b32_e32 v109, v2
	v_mov_b32_e32 v110, v2
	v_mov_b32_e32 v111, v2
	v_mov_b32_e32 v112, v2
	v_mov_b32_e32 v113, v2
	v_mov_b32_e32 v122, v2
	v_mov_b32_e32 v123, v2
	v_mov_b32_e32 v124, v2
	v_mov_b32_e32 v125, v2
	v_mov_b32_e32 v126, v2
	v_mov_b32_e32 v127, v2
	v_mov_b32_e32 v128, v2
	v_mov_b32_e32 v129, v2
	s_cmp_eq_u32 s73, 1
	s_cbranch_scc1 .LBB0_259
	s_add_u32 s14, s10, 0xfffc0080
	s_addc_u32 s15, s11, -1
	s_cmp_eq_u32 s49, 12
	s_cselect_b32 s27, s6, s15
	s_cselect_b32 s26, s36, s14
	v_add_u32_e32 v146, s33, v154
	s_cselect_b32 s15, s37, s43
	s_cselect_b32 s14, s40, s41
	s_add_i32 s51, 0, 0x14000
	ds_read_b128 v[142:145], v146
	ds_read_b128 v[158:161], v146 offset:1024
	ds_read_b128 v[162:165], v146 offset:2048
	ds_read_b128 v[166:169], v146 offset:3072
	v_add_u32_e32 v146, s51, v154
	ds_read_b128 v[170:173], v146
	ds_read_b128 v[174:177], v146 offset:1024
	ds_read_b128 v[178:181], v146 offset:2048
	ds_read_b128 v[182:185], v146 offset:3072
	v_lshl_add_u64 v[146:147], s[10:11], 0, v[138:139]
	s_add_i32 m0, s67, 0xc000
	ds_read_b128 v[186:189], v156
	ds_read_b128 v[190:193], v156 offset:1024
	ds_read_b128 v[194:197], v156 offset:2048
	ds_read_b128 v[198:201], v156 offset:3072
	ds_read_b128 v[202:205], v156 offset:4096
	ds_read_b128 v[206:209], v156 offset:5120
	ds_read_b128 v[210:213], v156 offset:6144
	ds_read_b128 v[214:217], v156 offset:7168
	v_lshl_add_u64 v[146:147], s[10:11], 0, v[140:141]
	s_add_i32 m0, s67, 0xe000
	s_nop 0
	s_waitcnt vmcnt(24)
	s_waitcnt lgkmcnt(0)
	s_barrier
	s_setprio 1
	s_waitcnt lgkmcnt(0)
	v_mfma_f32_16x16x32_bf16 v[126:129], v[142:145], v[186:189], v[126:129]
	v_mfma_f32_16x16x32_bf16 v[122:125], v[162:165], v[186:189], v[122:125]
	v_mfma_f32_16x16x32_bf16 v[110:113], v[142:145], v[194:197], v[110:113]
	v_mfma_f32_16x16x32_bf16 v[106:109], v[162:165], v[194:197], v[106:109]
	v_mfma_f32_16x16x32_bf16 v[94:97], v[142:145], v[202:205], v[94:97]
	v_mfma_f32_16x16x32_bf16 v[90:93], v[162:165], v[202:205], v[90:93]
	v_mfma_f32_16x16x32_bf16 v[78:81], v[142:145], v[210:213], v[78:81]
	v_mfma_f32_16x16x32_bf16 v[74:77], v[162:165], v[210:213], v[74:77]
	v_mfma_f32_16x16x32_bf16 v[126:129], v[158:161], v[190:193], v[126:129]
	v_mfma_f32_16x16x32_bf16 v[122:125], v[166:169], v[190:193], v[122:125]
	v_mfma_f32_16x16x32_bf16 v[110:113], v[158:161], v[198:201], v[110:113]
	v_mfma_f32_16x16x32_bf16 v[106:109], v[166:169], v[198:201], v[106:109]
	v_mfma_f32_16x16x32_bf16 v[94:97], v[158:161], v[206:209], v[94:97]
	v_mfma_f32_16x16x32_bf16 v[90:93], v[166:169], v[206:209], v[90:93]
	v_mfma_f32_16x16x32_bf16 v[78:81], v[158:161], v[214:217], v[78:81]
	v_mfma_f32_16x16x32_bf16 v[74:77], v[166:169], v[214:217], v[74:77]
	s_setprio 0
	s_setprio 1
	v_mfma_f32_16x16x32_bf16 v[118:121], v[170:173], v[186:189], v[118:121]
	v_mfma_f32_16x16x32_bf16 v[114:117], v[178:181], v[186:189], v[114:117]
	v_mfma_f32_16x16x32_bf16 v[102:105], v[170:173], v[194:197], v[102:105]
	v_mfma_f32_16x16x32_bf16 v[98:101], v[178:181], v[194:197], v[98:101]
	v_mfma_f32_16x16x32_bf16 v[86:89], v[170:173], v[202:205], v[86:89]
	v_mfma_f32_16x16x32_bf16 v[82:85], v[178:181], v[202:205], v[82:85]
	v_mfma_f32_16x16x32_bf16 v[70:73], v[170:173], v[210:213], v[70:73]
	v_mfma_f32_16x16x32_bf16 v[66:69], v[178:181], v[210:213], v[66:69]
	v_mfma_f32_16x16x32_bf16 v[118:121], v[174:177], v[190:193], v[118:121]
	v_mfma_f32_16x16x32_bf16 v[114:117], v[182:185], v[190:193], v[114:117]
	v_mfma_f32_16x16x32_bf16 v[102:105], v[174:177], v[198:201], v[102:105]
	v_mfma_f32_16x16x32_bf16 v[98:101], v[182:185], v[198:201], v[98:101]
	v_mfma_f32_16x16x32_bf16 v[86:89], v[174:177], v[206:209], v[86:89]
	v_mfma_f32_16x16x32_bf16 v[82:85], v[182:185], v[206:209], v[82:85]
	v_mfma_f32_16x16x32_bf16 v[70:73], v[174:177], v[214:217], v[70:73]
	v_mfma_f32_16x16x32_bf16 v[66:69], v[182:185], v[214:217], v[66:69]
	s_setprio 0
	s_barrier
	s_add_i32 s58, s33, s66
	v_lshl_add_u64 v[146:147], s[14:15], 0, v[132:133]
	s_mov_b32 m0, s58
	ds_read_b128 v[186:189], v156 offset:16384
	ds_read_b128 v[190:193], v156 offset:17408
	ds_read_b128 v[194:197], v156 offset:18432
	ds_read_b128 v[198:201], v156 offset:19456
	ds_read_b128 v[202:205], v156 offset:20480
	ds_read_b128 v[206:209], v156 offset:21504
	ds_read_b128 v[210:213], v156 offset:22528
	ds_read_b128 v[214:217], v156 offset:23552
	global_load_lds_dwordx4 v[146:147], off
	s_add_i32 m0, s58, 0x2000
	s_add_u32 s58, s14, 0x40000
	v_lshl_add_u64 v[148:149], s[14:15], 0, v[136:137]
	s_addc_u32 s59, s15, 0
	s_add_i32 s51, s51, s66
	global_load_lds_dwordx4 v[148:149], off
	v_lshl_add_u64 v[150:151], s[58:59], 0, v[132:133]
	s_mov_b32 m0, s51
	v_lshl_add_u64 v[152:153], s[26:27], 0, v[134:135]
	global_load_lds_dwordx4 v[150:151], off
	v_lshl_add_u64 v[150:151], s[58:59], 0, v[136:137]
	s_add_i32 m0, s51, 0x2000
	s_nop 0
	global_load_lds_dwordx4 v[150:151], off
	v_lshl_add_u64 v[150:151], s[26:27], 0, v[130:131]
	s_mov_b32 m0, s67
	s_nop 0
	global_load_lds_dwordx4 v[150:151], off
	s_mov_b32 m0, s68
	s_nop 0
	global_load_lds_dwordx4 v[152:153], off
	s_waitcnt vmcnt(24)
	s_waitcnt lgkmcnt(0)
	s_barrier
	s_setprio 1
	s_waitcnt lgkmcnt(0)
	v_mfma_f32_16x16x32_bf16 v[62:65], v[142:145], v[186:189], v[62:65]
	v_mfma_f32_16x16x32_bf16 v[58:61], v[162:165], v[186:189], v[58:61]
	v_mfma_f32_16x16x32_bf16 v[46:49], v[142:145], v[194:197], v[46:49]
	v_mfma_f32_16x16x32_bf16 v[42:45], v[162:165], v[194:197], v[42:45]
	v_mfma_f32_16x16x32_bf16 v[30:33], v[142:145], v[202:205], v[30:33]
	v_mfma_f32_16x16x32_bf16 v[26:29], v[162:165], v[202:205], v[26:29]
	v_mfma_f32_16x16x32_bf16 v[14:17], v[142:145], v[210:213], v[14:17]
	v_mfma_f32_16x16x32_bf16 v[10:13], v[162:165], v[210:213], v[10:13]
	v_mfma_f32_16x16x32_bf16 v[62:65], v[158:161], v[190:193], v[62:65]
	v_mfma_f32_16x16x32_bf16 v[58:61], v[166:169], v[190:193], v[58:61]
	v_mfma_f32_16x16x32_bf16 v[46:49], v[158:161], v[198:201], v[46:49]
	v_mfma_f32_16x16x32_bf16 v[42:45], v[166:169], v[198:201], v[42:45]
	v_mfma_f32_16x16x32_bf16 v[30:33], v[158:161], v[206:209], v[30:33]
	v_mfma_f32_16x16x32_bf16 v[26:29], v[166:169], v[206:209], v[26:29]
	v_mfma_f32_16x16x32_bf16 v[14:17], v[158:161], v[214:217], v[14:17]
	v_mfma_f32_16x16x32_bf16 v[10:13], v[166:169], v[214:217], v[10:13]
	s_setprio 0
	s_setprio 1
	v_mfma_f32_16x16x32_bf16 v[54:57], v[170:173], v[186:189], v[54:57]
	v_mfma_f32_16x16x32_bf16 v[50:53], v[178:181], v[186:189], v[50:53]
	v_mfma_f32_16x16x32_bf16 v[38:41], v[170:173], v[194:197], v[38:41]
	v_mfma_f32_16x16x32_bf16 v[34:37], v[178:181], v[194:197], v[34:37]
	v_mfma_f32_16x16x32_bf16 v[22:25], v[170:173], v[202:205], v[22:25]
	v_mfma_f32_16x16x32_bf16 v[18:21], v[178:181], v[202:205], v[18:21]
	v_mfma_f32_16x16x32_bf16 v[6:9], v[170:173], v[210:213], v[6:9]
	v_mfma_f32_16x16x32_bf16 v[2:5], v[178:181], v[210:213], v[2:5]
	v_mfma_f32_16x16x32_bf16 v[54:57], v[174:177], v[190:193], v[54:57]
	v_mfma_f32_16x16x32_bf16 v[50:53], v[182:185], v[190:193], v[50:53]
	v_mfma_f32_16x16x32_bf16 v[38:41], v[174:177], v[198:201], v[38:41]
	v_mfma_f32_16x16x32_bf16 v[34:37], v[182:185], v[198:201], v[34:37]
	v_mfma_f32_16x16x32_bf16 v[22:25], v[174:177], v[206:209], v[22:25]
	v_mfma_f32_16x16x32_bf16 v[18:21], v[182:185], v[206:209], v[18:21]
	v_mfma_f32_16x16x32_bf16 v[6:9], v[174:177], v[214:217], v[6:9]
	v_mfma_f32_16x16x32_bf16 v[2:5], v[182:185], v[214:217], v[2:5]
	s_setprio 0
	s_barrier
	s_add_i32 s51, 0, 0x18000
	v_add_u32_e32 v157, s51, v154
	s_add_i32 s58, 0, 0x1c000
	ds_read_b128 v[142:145], v157
	ds_read_b128 v[158:161], v157 offset:1024
	ds_read_b128 v[162:165], v157 offset:2048
	ds_read_b128 v[166:169], v157 offset:3072
	v_add_u32_e32 v157, s58, v154
	ds_read_b128 v[170:173], v157
	ds_read_b128 v[174:177], v157 offset:1024
	ds_read_b128 v[178:181], v157 offset:2048
	ds_read_b128 v[182:185], v157 offset:3072
	s_add_u32 s26, s26, 0x40000
	s_addc_u32 s27, s27, 0
	s_mov_b32 m0, s69
	v_lshl_add_u64 v[218:219], s[26:27], 0, v[130:131]
	ds_read_b128 v[186:189], v156 offset:32768
	ds_read_b128 v[190:193], v156 offset:33792
	ds_read_b128 v[194:197], v156 offset:34816
	ds_read_b128 v[198:201], v156 offset:35840
	ds_read_b128 v[202:205], v156 offset:36864
	ds_read_b128 v[206:209], v156 offset:37888
	ds_read_b128 v[210:213], v156 offset:38912
	ds_read_b128 v[214:217], v156 offset:39936
	global_load_lds_dwordx4 v[218:219], off
	v_lshl_add_u64 v[218:219], s[26:27], 0, v[134:135]
	s_mov_b32 m0, s70
	s_nop 0
	global_load_lds_dwordx4 v[218:219], off
	s_waitcnt vmcnt(24)
	s_waitcnt lgkmcnt(0)
	s_barrier
	s_setprio 1
	s_waitcnt lgkmcnt(0)
	v_mfma_f32_16x16x32_bf16 v[126:129], v[142:145], v[186:189], v[126:129]
	v_mfma_f32_16x16x32_bf16 v[122:125], v[162:165], v[186:189], v[122:125]
	v_mfma_f32_16x16x32_bf16 v[110:113], v[142:145], v[194:197], v[110:113]
	v_mfma_f32_16x16x32_bf16 v[106:109], v[162:165], v[194:197], v[106:109]
	v_mfma_f32_16x16x32_bf16 v[94:97], v[142:145], v[202:205], v[94:97]
	v_mfma_f32_16x16x32_bf16 v[90:93], v[162:165], v[202:205], v[90:93]
	v_mfma_f32_16x16x32_bf16 v[78:81], v[142:145], v[210:213], v[78:81]
	v_mfma_f32_16x16x32_bf16 v[74:77], v[162:165], v[210:213], v[74:77]
	v_mfma_f32_16x16x32_bf16 v[126:129], v[158:161], v[190:193], v[126:129]
	v_mfma_f32_16x16x32_bf16 v[122:125], v[166:169], v[190:193], v[122:125]
	v_mfma_f32_16x16x32_bf16 v[110:113], v[158:161], v[198:201], v[110:113]
	v_mfma_f32_16x16x32_bf16 v[106:109], v[166:169], v[198:201], v[106:109]
	v_mfma_f32_16x16x32_bf16 v[94:97], v[158:161], v[206:209], v[94:97]
	v_mfma_f32_16x16x32_bf16 v[90:93], v[166:169], v[206:209], v[90:93]
	v_mfma_f32_16x16x32_bf16 v[78:81], v[158:161], v[214:217], v[78:81]
	v_mfma_f32_16x16x32_bf16 v[74:77], v[166:169], v[214:217], v[74:77]
	s_setprio 0
	s_setprio 1
	v_mfma_f32_16x16x32_bf16 v[118:121], v[170:173], v[186:189], v[118:121]
	v_mfma_f32_16x16x32_bf16 v[114:117], v[178:181], v[186:189], v[114:117]
	v_mfma_f32_16x16x32_bf16 v[102:105], v[170:173], v[194:197], v[102:105]
	v_mfma_f32_16x16x32_bf16 v[98:101], v[178:181], v[194:197], v[98:101]
	v_mfma_f32_16x16x32_bf16 v[86:89], v[170:173], v[202:205], v[86:89]
	v_mfma_f32_16x16x32_bf16 v[82:85], v[178:181], v[202:205], v[82:85]
	v_mfma_f32_16x16x32_bf16 v[70:73], v[170:173], v[210:213], v[70:73]
	v_mfma_f32_16x16x32_bf16 v[66:69], v[178:181], v[210:213], v[66:69]
	v_mfma_f32_16x16x32_bf16 v[118:121], v[174:177], v[190:193], v[118:121]
	v_mfma_f32_16x16x32_bf16 v[114:117], v[182:185], v[190:193], v[114:117]
	v_mfma_f32_16x16x32_bf16 v[102:105], v[174:177], v[198:201], v[102:105]
	v_mfma_f32_16x16x32_bf16 v[98:101], v[182:185], v[198:201], v[98:101]
	v_mfma_f32_16x16x32_bf16 v[86:89], v[174:177], v[206:209], v[86:89]
	v_mfma_f32_16x16x32_bf16 v[82:85], v[182:185], v[206:209], v[82:85]
	v_mfma_f32_16x16x32_bf16 v[70:73], v[174:177], v[214:217], v[70:73]
	v_mfma_f32_16x16x32_bf16 v[66:69], v[182:185], v[214:217], v[66:69]
	s_setprio 0
	s_barrier
	s_add_i32 s26, s51, s66
	v_lshl_add_u64 v[146:147], v[146:147], 0, s[24:25]
	s_mov_b32 m0, s26
	ds_read_b128 v[186:189], v156 offset:49152
	ds_read_b128 v[190:193], v156 offset:50176
	ds_read_b128 v[194:197], v156 offset:51200
	ds_read_b128 v[198:201], v156 offset:52224
	ds_read_b128 v[202:205], v156 offset:53248
	ds_read_b128 v[206:209], v156 offset:54272
	ds_read_b128 v[210:213], v156 offset:55296
	ds_read_b128 v[214:217], v156 offset:56320
	global_load_lds_dwordx4 v[146:147], off
	s_add_i32 m0, s26, 0x2000
	s_add_u32 s14, s14, 0x40080
	v_lshl_add_u64 v[146:147], v[148:149], 0, s[24:25]
	s_addc_u32 s15, s15, 0
	s_add_i32 s26, s58, s66
	global_load_lds_dwordx4 v[146:147], off
	v_lshl_add_u64 v[146:147], s[14:15], 0, v[132:133]
	s_mov_b32 m0, s26
	s_nop 0
	global_load_lds_dwordx4 v[146:147], off
	v_lshl_add_u64 v[146:147], s[14:15], 0, v[136:137]
	s_add_i32 m0, s26, 0x2000
	s_nop 0
	global_load_lds_dwordx4 v[146:147], off
	v_lshl_add_u64 v[146:147], v[150:151], 0, s[24:25]
	s_mov_b32 m0, s71
	s_nop 0
	global_load_lds_dwordx4 v[146:147], off
	v_lshl_add_u64 v[146:147], v[152:153], 0, s[24:25]
	s_mov_b32 m0, s72
	s_nop 0
	global_load_lds_dwordx4 v[146:147], off
	s_waitcnt vmcnt(8)
	s_waitcnt lgkmcnt(0)
	s_barrier
	s_setprio 1
	s_waitcnt lgkmcnt(0)
	v_mfma_f32_16x16x32_bf16 v[62:65], v[142:145], v[186:189], v[62:65]
	v_mfma_f32_16x16x32_bf16 v[58:61], v[162:165], v[186:189], v[58:61]
	v_mfma_f32_16x16x32_bf16 v[46:49], v[142:145], v[194:197], v[46:49]
	v_mfma_f32_16x16x32_bf16 v[42:45], v[162:165], v[194:197], v[42:45]
	v_mfma_f32_16x16x32_bf16 v[30:33], v[142:145], v[202:205], v[30:33]
	v_mfma_f32_16x16x32_bf16 v[26:29], v[162:165], v[202:205], v[26:29]
	v_mfma_f32_16x16x32_bf16 v[14:17], v[142:145], v[210:213], v[14:17]
	v_mfma_f32_16x16x32_bf16 v[10:13], v[162:165], v[210:213], v[10:13]
	v_mfma_f32_16x16x32_bf16 v[62:65], v[158:161], v[190:193], v[62:65]
	v_mfma_f32_16x16x32_bf16 v[58:61], v[166:169], v[190:193], v[58:61]
	v_mfma_f32_16x16x32_bf16 v[46:49], v[158:161], v[198:201], v[46:49]
	v_mfma_f32_16x16x32_bf16 v[42:45], v[166:169], v[198:201], v[42:45]
	v_mfma_f32_16x16x32_bf16 v[30:33], v[158:161], v[206:209], v[30:33]
	v_mfma_f32_16x16x32_bf16 v[26:29], v[166:169], v[206:209], v[26:29]
	v_mfma_f32_16x16x32_bf16 v[14:17], v[158:161], v[214:217], v[14:17]
	v_mfma_f32_16x16x32_bf16 v[10:13], v[166:169], v[214:217], v[10:13]
	s_setprio 0
	s_setprio 1
	v_mfma_f32_16x16x32_bf16 v[54:57], v[170:173], v[186:189], v[54:57]
	v_mfma_f32_16x16x32_bf16 v[50:53], v[178:181], v[186:189], v[50:53]
	v_mfma_f32_16x16x32_bf16 v[38:41], v[170:173], v[194:197], v[38:41]
	v_mfma_f32_16x16x32_bf16 v[34:37], v[178:181], v[194:197], v[34:37]
	v_mfma_f32_16x16x32_bf16 v[22:25], v[170:173], v[202:205], v[22:25]
	v_mfma_f32_16x16x32_bf16 v[18:21], v[178:181], v[202:205], v[18:21]
	v_mfma_f32_16x16x32_bf16 v[6:9], v[170:173], v[210:213], v[6:9]
	v_mfma_f32_16x16x32_bf16 v[2:5], v[178:181], v[210:213], v[2:5]
	v_mfma_f32_16x16x32_bf16 v[54:57], v[174:177], v[190:193], v[54:57]
	v_mfma_f32_16x16x32_bf16 v[50:53], v[182:185], v[190:193], v[50:53]
	v_mfma_f32_16x16x32_bf16 v[38:41], v[174:177], v[198:201], v[38:41]
	v_mfma_f32_16x16x32_bf16 v[34:37], v[182:185], v[198:201], v[34:37]
	v_mfma_f32_16x16x32_bf16 v[22:25], v[174:177], v[206:209], v[22:25]
	v_mfma_f32_16x16x32_bf16 v[18:21], v[182:185], v[206:209], v[18:21]
	v_mfma_f32_16x16x32_bf16 v[6:9], v[174:177], v[214:217], v[6:9]
	v_mfma_f32_16x16x32_bf16 v[2:5], v[182:185], v[214:217], v[2:5]
	s_setprio 0
	s_barrier
	s_add_i32 s49, s49, 2
	s_add_u32 s10, s10, 0x100
	s_addc_u32 s11, s11, 0
	s_add_u32 s41, s41, 0x100
	s_addc_u32 s43, s43, 0
	.p2align 8

.LBB0_747:
	s_and_b64 vcc, exec, s[10:11]
	s_cbranch_vccz .LBB0_751
	v_mov_b32_e32 v10, v232
	s_load_dwordx8 s[52:59], s[44:45], 0x60
	v_and_b32_e32 v181, 63, v10
	v_readlane_b32 s10, v255, 20
	v_mov_b32_e32 v3, v0
	s_load_dwordx2 s[42:43], s[44:45], 0xb0
	v_or_b32_e32 v2, s10, v181
	v_lshlrev_b64 v[2:3], 2, v[2:3]
	s_waitcnt lgkmcnt(0)
	v_lshl_add_u64 v[4:5], s[52:53], 0, v[2:3]
	global_load_dword v11, v[4:5], off
	v_lshl_add_u64 v[4:5], s[54:55], 0, v[2:3]
	global_load_dword v12, v[4:5], off
	v_lshl_add_u64 v[4:5], s[56:57], 0, v[2:3]
	v_lshl_add_u64 v[2:3], s[58:59], 0, v[2:3]
	global_load_dword v13, v[4:5], off
	global_load_dword v14, v[2:3], off
	s_add_i32 s6, s37, s48
	s_lshl_b32 s14, s36, 7
	s_lshl_b32 s30, s36, 8
	v_readlane_b32 s11, v255, 21
	s_add_u32 s10, s42, s47
	s_addc_u32 s11, s43, s46
	s_add_u32 s36, s10, s30
	s_addc_u32 s37, s11, 0
	s_lshl_b32 s10, s27, 10
	s_or_b32 s10, s14, s10
	s_mul_hi_i32 s11, s10, 0x2200
	s_mulk_i32 s10, 0x2200
	v_ashrrev_i32_e32 v50, 4, v10
	s_add_u32 s10, s42, s10
	v_ashrrev_i32_e32 v51, 31, v50
	v_and_b32_e32 v177, 15, v10
	s_addc_u32 s11, s43, s11
	v_lshlrev_b64 v[52:53], 11, v[50:51]
	s_add_u32 s40, s10, 0xe010000
	v_lshl_add_u64 v[2:3], s[36:37], 0, v[52:53]
	v_lshlrev_b32_e32 v124, 4, v177
	v_mov_b32_e32 v125, v0
	s_addc_u32 s41, s11, 0
	v_lshl_add_u64 v[2:3], v[2:3], 0, v[124:125]
	s_mov_b32 s15, 0x16810000
	v_mov_b64_e32 v[4:5], s[40:41]
	s_movk_i32 s35, 0x2200
	v_add_co_u32_e32 v6, vcc, s15, v2
	v_mad_i64_i32 v[4:5], s[36:37], v50, s35, v[4:5]
	s_nop 0
	v_addc_co_u32_e32 v7, vcc, 0, v3, vcc
	s_mov_b32 s15, 0x16820000
	v_lshl_add_u64 v[4:5], v[4:5], 0, v[124:125]
	global_load_dwordx4 v[18:21], v[6:7], off
	global_load_dwordx4 v[22:25], v[4:5], off
	v_add_co_u32_e32 v6, vcc, s15, v2
	s_mov_b32 s15, 0x44000
	s_nop 0
	v_addc_co_u32_e32 v7, vcc, 0, v3, vcc
	v_add_co_u32_e32 v8, vcc, s15, v4
	s_mov_b32 s15, 0x16830000
	s_nop 0
	v_addc_co_u32_e32 v9, vcc, 0, v5, vcc
	global_load_dwordx4 v[26:29], v[6:7], off
	global_load_dwordx4 v[30:33], v[8:9], off
	v_add_co_u32_e32 v6, vcc, s15, v2
	s_mov_b32 s15, 0x88000
	s_nop 0
	v_addc_co_u32_e32 v7, vcc, 0, v3, vcc
	v_add_co_u32_e32 v8, vcc, s15, v4
	s_mov_b32 s15, 0x16840000
	s_nop 0
	v_addc_co_u32_e32 v9, vcc, 0, v5, vcc
	v_add_co_u32_e32 v2, vcc, s15, v2
	s_mov_b32 s15, 0xcc000
	s_nop 0
	v_addc_co_u32_e32 v3, vcc, 0, v3, vcc
	v_add_co_u32_e32 v4, vcc, s15, v4
	global_load_dwordx4 v[34:37], v[6:7], off
	global_load_dwordx4 v[38:41], v[8:9], off
	v_addc_co_u32_e32 v5, vcc, 0, v5, vcc
	global_load_dwordx4 v[42:45], v[2:3], off
	global_load_dwordx4 v[46:49], v[4:5], off
	v_ashrrev_i32_e32 v4, 2, v10
	v_and_b32_e32 v4, 0xffffffe0, v4
	v_add_u32_e32 v180, s6, v4
	v_ashrrev_i32_e32 v182, 6, v10
	v_and_b32_e32 v179, 1, v182
	v_mov_b32_e32 v55, v0
	v_lshlrev_b32_e32 v54, 7, v179
	s_waitcnt vmcnt(10)
	v_mul_f32_e32 v2, v11, v12
	ds_bpermute_b32 v2, v1, v2
	v_and_b32_e32 v56, 48, v10
	v_mov_b32_e32 v57, v0
	s_waitcnt vmcnt(8)
	v_mul_f32_e32 v3, v13, v14
	ds_bpermute_b32 v3, v1, v3
	s_waitcnt lgkmcnt(1)
	v_fmac_f32_e32 v2, v11, v12
	ds_bpermute_b32 v5, v176, v2
	s_mov_b32 s6, 0x14610000
	s_mov_b64 s[36:37], 0x14610000
	s_waitcnt lgkmcnt(1)
	v_fmac_f32_e32 v3, v13, v14
	ds_bpermute_b32 v6, v176, v3
	s_waitcnt lgkmcnt(1)
	v_add_f32_e32 v4, v2, v5
	v_and_b32_e32 v2, 31, v223
	v_or_b32_e32 v2, v180, v2
	v_bfe_u32 v178, v10, 4, 2
	v_lshlrev_b32_e32 v51, 1, v50
	s_waitcnt lgkmcnt(0)
	v_add_f32_e32 v5, v3, v6
	ds_bpermute_b32 v6, v175, v4
	ds_bpermute_b32 v7, v175, v5
	v_ashrrev_i32_e32 v3, 31, v2
	v_lshlrev_b64 v[2:3], 11, v[2:3]
	v_lshl_add_u64 v[2:3], s[42:43], 0, v[2:3]
	s_waitcnt lgkmcnt(1)
	v_add_f32_e32 v4, v4, v6
	s_waitcnt lgkmcnt(0)
	v_add_f32_e32 v5, v5, v7
	ds_bpermute_b32 v6, v174, v4
	ds_bpermute_b32 v7, v174, v5
	v_lshl_add_u64 v[2:3], v[2:3], 0, s[30:31]
	v_lshl_add_u64 v[2:3], v[2:3], 0, v[54:55]
	v_lshrrev_b32_e32 v55, 1, v50
	s_waitcnt lgkmcnt(1)
	v_add_f32_e32 v132, v4, v6
	s_waitcnt lgkmcnt(0)
	v_add_f32_e32 v133, v5, v7
	v_and_b32_e32 v56, 32, v232
	v_lshrrev_b32_e32 v56, 1, v56
	v_lshl_add_u64 v[6:7], v[2:3], 0, v[56:57]
	v_add_co_u32_e32 v4, vcc, s6, v6
	s_mov_b32 s6, 0x14610020
	s_nop 0
	v_addc_co_u32_e32 v5, vcc, 0, v7, vcc
	v_lshl_add_u64 v[2:3], v[6:7], 0, s[36:37]
	v_add_co_u32_e32 v6, vcc, s6, v6
	global_load_dwordx4 v[10:13], v[4:5], off
	s_nop 0
	global_load_dwordx4 v[2:5], v[2:3], off offset:64
	v_addc_co_u32_e32 v7, vcc, 0, v7, vcc
	global_load_dwordx4 v[14:17], v[6:7], off
	s_nop 0
	global_load_dwordx4 v[6:9], v[6:7], off offset:64
	v_and_b32_e32 v51, 8, v51
	v_and_b32_e32 v55, 4, v55
	v_and_b32_e32 v57, 0xffffff3, v50
	v_or3_b32 v51, v57, v51, v55
	s_movk_i32 s6, 0x110
	v_mul_lo_u32 v55, v50, s6
	v_mad_u64_u32 v[126:127], s[36:37], v51, s6, v[124:125]
	s_mov_b32 s6, 0x11000
	v_add3_u32 v127, v55, v124, s6
	v_add_u32_e32 v51, 0, v126
	v_add_u32_e32 v55, 0, v127
	s_waitcnt vmcnt(11)
	ds_write_b128 v51, v[18:21]
	s_waitcnt vmcnt(10)
	ds_write_b128 v55, v[22:25]
	s_waitcnt vmcnt(9)
	ds_write_b128 v51, v[26:29] offset:8704
	s_waitcnt vmcnt(8)
	ds_write_b128 v55, v[30:33] offset:8704
	s_waitcnt vmcnt(7)
	ds_write_b128 v51, v[34:37] offset:17408
	s_waitcnt vmcnt(6)
	ds_write_b128 v55, v[38:41] offset:17408
	s_waitcnt vmcnt(5)
	ds_write_b128 v51, v[42:45] offset:26112
	s_waitcnt vmcnt(4)
	ds_write_b128 v55, v[46:49] offset:26112
	s_add_i32 s6, 0, 0x11000
	v_mul_u32_u24_e32 v19, 0x110, v177
	v_add3_u32 v183, s6, v56, v19
	s_lshl_b32 s6, s26, 3
	s_and_b32 s6, s6, 0x700
	ds_bpermute_b32 v134, v173, v132
	ds_bpermute_b32 v135, v173, v133
	s_add_u32 s6, s42, s6
	v_add_u32_e32 v18, 0, v54
	s_addc_u32 s18, s43, 0
	v_add3_u32 v137, v18, v56, v19
	s_add_u32 s26, s6, s47
	v_mov_b64_e32 v[18:19], s[10:11]
	s_addc_u32 s27, s18, s46
	v_mad_i64_i32 v[130:131], s[10:11], v50, s35, v[18:19]
	v_mov_b32_e32 v18, 0
	s_mov_b32 s15, 0
	v_lshl_add_u64 v[128:129], s[26:27], 0, v[52:53]
	v_mov_b32_e32 v19, v18
	v_mov_b32_e32 v20, v18
	v_mov_b32_e32 v21, v18
	v_mov_b32_e32 v22, v18
	v_mov_b32_e32 v23, v18
	v_mov_b32_e32 v24, v18
	v_mov_b32_e32 v25, v18
	v_mov_b32_e32 v26, v18
	v_mov_b32_e32 v27, v18
	v_mov_b32_e32 v28, v18
	v_mov_b32_e32 v29, v18
	v_mov_b32_e32 v30, v18
	v_mov_b32_e32 v31, v18
	v_mov_b32_e32 v32, v18
	v_mov_b32_e32 v33, v18
	v_mov_b32_e32 v38, v18
	v_mov_b32_e32 v39, v18
	v_mov_b32_e32 v40, v18
	v_mov_b32_e32 v41, v18
	v_mov_b32_e32 v46, v18
	v_mov_b32_e32 v47, v18
	v_mov_b32_e32 v48, v18
	v_mov_b32_e32 v49, v18
	v_mov_b32_e32 v62, v18
	v_mov_b32_e32 v63, v18
	v_mov_b32_e32 v64, v18
	v_mov_b32_e32 v65, v18
	v_mov_b32_e32 v74, v18
	v_mov_b32_e32 v75, v18
	v_mov_b32_e32 v76, v18
	v_mov_b32_e32 v77, v18
	v_mov_b32_e32 v34, v18
	v_mov_b32_e32 v35, v18
	v_mov_b32_e32 v36, v18
	v_mov_b32_e32 v37, v18
	v_mov_b32_e32 v42, v18
	v_mov_b32_e32 v43, v18
	v_mov_b32_e32 v44, v18
	v_mov_b32_e32 v45, v18
	v_mov_b32_e32 v50, v18
	v_mov_b32_e32 v51, v18
	v_mov_b32_e32 v52, v18
	v_mov_b32_e32 v53, v18
	v_mov_b32_e32 v54, v18
	v_mov_b32_e32 v55, v18
	v_mov_b32_e32 v56, v18
	v_mov_b32_e32 v57, v18
	v_mov_b32_e32 v58, v18
	v_mov_b32_e32 v59, v18
	v_mov_b32_e32 v60, v18
	v_mov_b32_e32 v61, v18
	v_mov_b32_e32 v66, v18
	v_mov_b32_e32 v67, v18
	v_mov_b32_e32 v68, v18
	v_mov_b32_e32 v69, v18
	v_mov_b32_e32 v70, v18
	v_mov_b32_e32 v71, v18
	v_mov_b32_e32 v72, v18
	v_mov_b32_e32 v73, v18
	v_mov_b32_e32 v78, v18
	v_mov_b32_e32 v79, v18
	v_mov_b32_e32 v80, v18
	v_mov_b32_e32 v81, v18
	v_mov_b32_e32 v122, v18
	v_mov_b32_e32 v123, v18
	s_mov_b32 s11, 0xe054000
	s_mov_b32 s18, 0x16870000
	s_mov_b32 s26, 0xe098000
	s_mov_b32 s27, 0x16880000
	s_mov_b32 s30, 0xe0dc000
	s_mov_b64 s[36:37], 0x40000
	s_waitcnt lgkmcnt(0)
	s_barrier
	s_waitcnt vmcnt(0) lgkmcnt(0)
	v_writelane_b32 v175, s64, 0
	v_writelane_b32 v175, s65, 1
	v_writelane_b32 v175, s66, 2
	v_writelane_b32 v175, s67, 3
	v_writelane_b32 v175, s68, 4
	v_writelane_b32 v175, s69, 5
	v_writelane_b32 v175, s70, 6
	v_writelane_b32 v175, s71, 7
	v_writelane_b32 v175, s72, 8
	v_writelane_b32 v175, s73, 9
	v_writelane_b32 v175, s74, 10
	v_writelane_b32 v175, s75, 11
	v_writelane_b32 v175, s76, 12
	v_writelane_b32 v175, s77, 13
	v_writelane_b32 v175, s78, 14
	v_writelane_b32 v175, s79, 15
	v_lshl_add_u64 v[138:139], v[128:129], 0, v[124:125]
	v_lshl_add_u64 v[140:141], v[130:131], 0, v[124:125]
	s_nop 1
	v_readfirstlane_b32 s64, v138
	v_readfirstlane_b32 s65, v139
	v_readfirstlane_b32 s72, v140
	v_readfirstlane_b32 s73, v141
	s_nop 3
	v_subrev_u32_e32 v124, s64, v138
	v_subrev_u32_e32 v125, s72, v140
	s_add_u32 s66, s64, s97
	s_addc_u32 s67, s65, 0
	s_add_u32 s68, s64, s18
	s_addc_u32 s69, s65, 0
	s_add_u32 s70, s64, s27
	s_addc_u32 s71, s65, 0
	s_add_u32 s64, s64, s96
	s_addc_u32 s65, s65, 0
	s_add_u32 s74, s72, s11
	s_addc_u32 s75, s73, 0
	s_add_u32 s74, s74, 0x100
	s_addc_u32 s75, s75, 0
	s_add_u32 s76, s72, s26
	s_addc_u32 s77, s73, 0
	s_add_u32 s76, s76, 0x100
	s_addc_u32 s77, s77, 0
	s_add_u32 s78, s72, s30
	s_addc_u32 s79, s73, 0
	s_add_u32 s78, s78, 0x100
	s_addc_u32 s79, s79, 0
	s_add_u32 s72, s72, s91
	s_addc_u32 s73, s73, 0
	s_add_u32 s72, s72, 0x100
	s_addc_u32 s73, s73, 0
	v_and_b32_e32 v137, 31, v223
	v_mul_u32_u24_e32 v137, 0x110, v137
	v_lshrrev_b32_e32 v183, 5, v223
	v_lshl_add_u32 v137, v183, 4, v137
	v_add_u32_e32 v183, 0x11000, v137
	v_lshl_add_u32 v137, v179, 7, v137
	s_mov_b32 s15, 0
	s_nop 4
	.p2align 8

.LBB0_914:
	s_add_u32 s10, s10, 0x40080
	s_addc_u32 s11, s11, 0
	s_add_u32 s44, s14, 0x100
	s_addc_u32 s45, s15, 0
	s_mov_b32 s55, -2
	.p2align 8

.LBB0_1102:
	s_add_u32 s48, s48, 0x40080
	s_addc_u32 s49, s49, 0
	s_add_u32 s6, s14, 0x100
	v_mov_b32_e32 v2, 0
	s_addc_u32 s37, s15, 0
	s_mov_b32 s43, -2
	v_mov_b32_e32 v3, v2
	v_mov_b32_e32 v4, v2
	v_mov_b32_e32 v5, v2
	v_mov_b32_e32 v6, v2
	v_mov_b32_e32 v7, v2
	v_mov_b32_e32 v8, v2
	v_mov_b32_e32 v9, v2
	v_mov_b32_e32 v10, v2
	v_mov_b32_e32 v11, v2
	v_mov_b32_e32 v12, v2
	v_mov_b32_e32 v13, v2
	v_mov_b32_e32 v22, v2
	v_mov_b32_e32 v23, v2
	v_mov_b32_e32 v24, v2
	v_mov_b32_e32 v25, v2
	v_mov_b32_e32 v26, v2
	v_mov_b32_e32 v27, v2
	v_mov_b32_e32 v28, v2
	v_mov_b32_e32 v29, v2
	v_mov_b32_e32 v38, v2
	v_mov_b32_e32 v39, v2
	v_mov_b32_e32 v40, v2
	v_mov_b32_e32 v41, v2
	v_mov_b32_e32 v42, v2
	v_mov_b32_e32 v43, v2
	v_mov_b32_e32 v44, v2
	v_mov_b32_e32 v45, v2
	v_mov_b32_e32 v54, v2
	v_mov_b32_e32 v55, v2
	v_mov_b32_e32 v56, v2
	v_mov_b32_e32 v57, v2
	v_mov_b32_e32 v14, v2
	v_mov_b32_e32 v15, v2
	v_mov_b32_e32 v16, v2
	v_mov_b32_e32 v17, v2
	v_mov_b32_e32 v18, v2
	v_mov_b32_e32 v19, v2
	v_mov_b32_e32 v20, v2
	v_mov_b32_e32 v21, v2
	v_mov_b32_e32 v30, v2
	v_mov_b32_e32 v31, v2
	v_mov_b32_e32 v32, v2
	v_mov_b32_e32 v33, v2
	v_mov_b32_e32 v34, v2
	v_mov_b32_e32 v35, v2
	v_mov_b32_e32 v36, v2
	v_mov_b32_e32 v37, v2
	v_mov_b32_e32 v46, v2
	v_mov_b32_e32 v47, v2
	v_mov_b32_e32 v48, v2
	v_mov_b32_e32 v49, v2
	v_mov_b32_e32 v50, v2
	v_mov_b32_e32 v51, v2
	v_mov_b32_e32 v52, v2
	v_mov_b32_e32 v53, v2
	v_mov_b32_e32 v58, v2
	v_mov_b32_e32 v59, v2
	v_mov_b32_e32 v60, v2
	v_mov_b32_e32 v61, v2
	v_mov_b32_e32 v62, v2
	v_mov_b32_e32 v63, v2
	v_mov_b32_e32 v64, v2
	v_mov_b32_e32 v65, v2
	v_mov_b32_e32 v66, v2
	v_mov_b32_e32 v67, v2
	v_mov_b32_e32 v68, v2
	v_mov_b32_e32 v69, v2
	v_mov_b32_e32 v70, v2
	v_mov_b32_e32 v71, v2
	v_mov_b32_e32 v72, v2
	v_mov_b32_e32 v73, v2
	v_mov_b32_e32 v74, v2
	v_mov_b32_e32 v75, v2
	v_mov_b32_e32 v76, v2
	v_mov_b32_e32 v77, v2
	v_mov_b32_e32 v86, v2
	v_mov_b32_e32 v87, v2
	v_mov_b32_e32 v88, v2
	v_mov_b32_e32 v89, v2
	v_mov_b32_e32 v90, v2
	v_mov_b32_e32 v91, v2
	v_mov_b32_e32 v92, v2
	v_mov_b32_e32 v93, v2
	v_mov_b32_e32 v102, v2
	v_mov_b32_e32 v103, v2
	v_mov_b32_e32 v104, v2
	v_mov_b32_e32 v105, v2
	v_mov_b32_e32 v106, v2
	v_mov_b32_e32 v107, v2
	v_mov_b32_e32 v108, v2
	v_mov_b32_e32 v109, v2
	v_mov_b32_e32 v118, v2
	v_mov_b32_e32 v119, v2
	v_mov_b32_e32 v120, v2
	v_mov_b32_e32 v121, v2
	v_mov_b32_e32 v78, v2
	v_mov_b32_e32 v79, v2
	v_mov_b32_e32 v80, v2
	v_mov_b32_e32 v81, v2
	v_mov_b32_e32 v82, v2
	v_mov_b32_e32 v83, v2
	v_mov_b32_e32 v84, v2
	v_mov_b32_e32 v85, v2
	v_mov_b32_e32 v94, v2
	v_mov_b32_e32 v95, v2
	v_mov_b32_e32 v96, v2
	v_mov_b32_e32 v97, v2
	v_mov_b32_e32 v98, v2
	v_mov_b32_e32 v99, v2
	v_mov_b32_e32 v100, v2
	v_mov_b32_e32 v101, v2
	v_mov_b32_e32 v110, v2
	v_mov_b32_e32 v111, v2
	v_mov_b32_e32 v112, v2
	v_mov_b32_e32 v113, v2
	v_mov_b32_e32 v114, v2
	v_mov_b32_e32 v115, v2
	v_mov_b32_e32 v116, v2
	v_mov_b32_e32 v117, v2
	v_mov_b32_e32 v122, v2
	v_mov_b32_e32 v123, v2
	v_mov_b32_e32 v124, v2
	v_mov_b32_e32 v125, v2
	v_mov_b32_e32 v126, v2
	v_mov_b32_e32 v127, v2
	v_mov_b32_e32 v128, v2
	v_mov_b32_e32 v129, v2
	.p2align 8
